# both wave groups of EVERY non-recurrence workgroup decode for their first two pulls
# baseline (speedup 1.0000x reference)
; #define LAS __attribute__((address_space(3)))
; __device__ __forceinline__ void p3_scan_and_sb(const Params& P, float* lds) {
;     ...
;     } else {
;         const int grp = wave >> 2, gw = wave & 3;
;         volatile LAS unsigned* gctl = (volatile LAS unsigned*)((LAS unsigned char*)lds + LDS_CTL + 32);
;         if (tid < 8) gctl[tid] = 0u;
;         __syncthreads();
;         sba::Grp4 G; G.ctr = gctl + grp; G.gen = 0u;
;         if (grp == 1) sb_decode_wave_loop(P, lds);
.LBB0_939:
	s_cmp_lt_i32 s60, 4
	s_cselect_b64 s[0:1], -1, 0
	s_cmp_gt_i32 s61, 3
	s_cselect_b64 s[2:3], -1, 0
	s_and_b64 s[34:35], s[0:1], s[2:3]
	s_andn2_b64 vcc, exec, s[34:35]
	s_cbranch_vccnz .LBB0_1576
	v_writelane_b32 v252, s34, 54
	s_cmpk_lt_u32 s56, 0x60
	v_and_b32_e32 v1, 63, v0
	v_writelane_b32 v252, s35, 55
	v_writelane_b32 v252, s80, 56
	s_cselect_b64 s[52:53], -1, 0
	s_cmpk_gt_u32 s56, 0x5f
	v_writelane_b32 v252, s81, 57
	v_writelane_b32 v252, s56, 53
	v_writelane_b32 v252, s60, 51
	s_mov_b64 s[0:1], -1
	s_waitcnt vmcnt(0)
	v_writelane_b32 v252, s61, 52
	s_barrier
	v_writelane_b32 v252, s57, 50
	s_cbranch_scc0 .LBB0_1203
	v_writelane_b32 v252, s52, 58
	v_cmp_gt_u32_e32 vcc, 8, v0
	s_nop 0
	v_writelane_b32 v252, s53, 59
	s_and_saveexec_b64 s[0:1], vcc
	v_lshl_add_u32 v2, v0, 2, 0
	v_add_u32_e32 v2, 0x26020, v2
	v_mov_b32_e32 v3, 0
	ds_write_b32 v2, v3
	s_or_b64 exec, exec, s[0:1]
	v_lshrrev_b32_e32 v94, 8, v0
	s_waitcnt lgkmcnt(0)
	s_barrier
	v_cmp_eq_u32_e32 vcc, 1, v94
	s_mov_b64 s[0:1], exec
	v_writelane_b32 v252, s0, 60
	s_nop 1
	v_writelane_b32 v252, s1, 61
	s_cmpk_gt_u32 s56, 0x5f
	s_cselect_b64 s[2:3], exec, 0
	s_or_b64 vcc, vcc, s[2:3]
	s_and_b64 s[0:1], s[0:1], vcc
	s_mov_b64 exec, s[0:1]
	s_cbranch_execz .LBB0_1092
	v_readfirstlane_b32 s2, v94
	s_cmp_eq_u32 s2, 0
	s_cselect_b32 s100, 1, 0x7fffffff
	s_add_u32 s0, s78, 0x3900
	s_addc_u32 s1, s79, 0
	v_writelane_b32 v252, s0, 62
	v_mov_b32_e32 v95, 0
	v_cmp_eq_u32_e64 s[4:5], 0, v1
	v_writelane_b32 v252, s1, 63
	s_and_saveexec_b64 s[0:1], s[4:5]
	v_readlane_b32 s22, v252, 48
	v_readlane_b32 s23, v252, 49
	s_cbranch_execz .LBB0_948
	s_mov_b64 s[6:7], exec
	v_mbcnt_lo_u32_b32 v2, s6, 0
	v_mbcnt_hi_u32_b32 v2, s7, v2
	v_cmp_eq_u32_e32 vcc, 0, v2
	s_and_saveexec_b64 s[2:3], vcc
	s_cbranch_execz .LBB0_947
	s_bcnt1_i32_b64 s6, s[6:7]
	s_lshl_b32 s6, s6, 1
	v_mov_b32_e32 v4, s6
	v_readlane_b32 s6, v252, 62
	v_mov_b32_e32 v3, 0
	v_readlane_b32 s7, v252, 63
	s_nop 4
	global_atomic_add v3, v3, v4, s[6:7] sc0
